# prep waves of the prompt scan now prefetch per-step operands two chunks ahead (shadow register set + copy), dropped the vmcnt waits that serialised each chunk behind one memory latency
# speedup vs baseline: 1.0677x; 1.0169x over previous
.LBB0_950:
	s_or_b64 exec, exec, s[4:5]
	s_waitcnt lgkmcnt(1)
	v_add_f32_e32 v7, v11, v45
	v_mul_f32_e32 v11, 0x4f800000, v7
	v_cmp_gt_f32_e32 vcc, s28, v7
	v_add_u32_e32 v5, 0x3000, v5
	ds_write2_b64 v5, v[16:17], v[28:29] offset1:32
	v_cndmask_b32_e32 v7, v7, v11, vcc
	v_sqrt_f32_e32 v11, v7
	s_or_b32 s8, s8, 32
	s_movk_i32 s12, 0xf000
	v_mov_b32_e32 v45, 0
	v_add_u32_e32 v18, -1, v11
	v_fma_f32 v19, -v18, v11, v7
	v_cmp_ge_f32_e64 s[4:5], 0, v19
	v_add_u32_e32 v19, 1, v11
	s_add_i32 s30, s27, s6
	v_cndmask_b32_e64 v18, v11, v18, s[4:5]
	v_fma_f32 v11, -v19, v11, v7
	v_cmp_lt_f32_e64 s[4:5], 0, v11
	s_add_i32 s30, s30, -4
	v_lshrrev_b32_e32 v111, 3, v100
	v_cndmask_b32_e64 v11, v18, v19, s[4:5]
	v_mul_f32_e32 v18, 0x37800000, v11
	v_cndmask_b32_e32 v11, v11, v18, vcc
	v_cmp_class_f32_e32 vcc, v7, v103
	s_mov_b64 s[14:15], 0x10440000
	s_mov_b32 s17, s7
	v_cndmask_b32_e32 v7, v11, v7, vcc
	v_max_f32_e32 v7, 0x2b8cbccc, v7
	v_div_scale_f32 v11, s[4:5], v7, v7, 1.0
	v_rcp_f32_e32 v18, v11
	s_movk_i32 s5, 0x1000
	s_movk_i32 s4, 0x1a40
	s_mov_b64 s[18:19], 0x12520000
	v_fma_f32 v19, -v11, v18, 1.0
	v_fmac_f32_e32 v18, v19, v18
	v_div_scale_f32 v19, vcc, 1.0, v7, 1.0
	v_mul_f32_e32 v20, v19, v18
	v_fma_f32 v21, -v11, v20, v19
	v_fmac_f32_e32 v20, v21, v18
	v_fma_f32 v11, -v11, v20, v19
	v_div_fmas_f32 v11, v11, v18, v20
	v_div_fixup_f32 v18, v11, v7, 1.0
	v_pk_mul_f32 v[16:17], v[26:27], v[18:19] op_sel_hi:[1,0] neg_lo:[0,1] neg_hi:[0,1]
	v_mov_b32_e32 v7, v45
	v_pk_mul_f32 v[18:19], v[16:17], v[24:25] neg_lo:[1,0] neg_hi:[1,0]
	ds_write2_b64 v5, v[16:17], v[18:19] offset0:64 offset1:96
	ds_write2_b64 v5, v[22:23], v[30:31] offset0:128 offset1:160
	v_lshl_add_u64 v[16:17], s[8:9], 0, v[2:3]
	v_mul_hi_i32_i24_e32 v19, 0x1a40, v16
	v_mul_i32_i24_e32 v18, 0x1a40, v16
	v_lshl_add_u64 v[18:19], v[8:9], 0, v[18:19]
	v_add_co_u32_e32 v20, vcc, s5, v18
	v_lshlrev_b64 v[24:25], 12, v[16:17]
	s_nop 0
	v_addc_co_u32_e32 v21, vcc, 0, v19, vcc
	v_lshlrev_b64 v[16:17], 11, v[16:17]
	v_add_co_u32_e32 v22, vcc, s12, v18
	v_lshl_add_u64 v[16:17], v[14:15], 0, v[16:17]
	s_nop 0
	v_addc_co_u32_e32 v23, vcc, -1, v19, vcc
	v_lshl_add_u64 v[24:25], v[12:13], 0, v[24:25]
	global_load_dword v112, v[18:19], off
	global_load_dword v113, v[18:19], off offset:2048
	global_load_dword v114, v[20:21], off
	global_load_dword v115, v[22:23], off offset:-2624
	global_load_dword v116, v[22:23], off offset:-576
	global_load_dwordx2 v[48:49], v[24:25], off
	global_load_dword v120, v[16:17], off
	global_load_dword v119, v[18:19], off offset:-2624
	v_add_u32_e32 v16, s8, v6
	v_mad_u64_u32 v[18:19], s[10:11], v16, s4, v[8:9]
	v_mov_b32_e32 v17, v45
	v_add_co_u32_e32 v20, vcc, s5, v18
	v_lshlrev_b64 v[24:25], 12, v[16:17]
	s_nop 0
	v_addc_co_u32_e32 v21, vcc, 0, v19, vcc
	v_lshlrev_b64 v[16:17], 11, v[16:17]
	v_add_co_u32_e32 v22, vcc, s12, v18
	v_lshl_add_u64 v[16:17], v[14:15], 0, v[16:17]
	s_nop 0
	v_addc_co_u32_e32 v23, vcc, -1, v19, vcc
	v_lshl_add_u64 v[24:25], v[12:13], 0, v[24:25]
	global_load_dword v128, v[18:19], off
	global_load_dword v121, v[18:19], off offset:2048
	global_load_dword v129, v[20:21], off
	global_load_dword v122, v[22:23], off offset:-2624
	global_load_dword v123, v[22:23], off offset:-576
	global_load_dwordx2 v[50:51], v[24:25], off
	global_load_dword v125, v[16:17], off
	global_load_dword v124, v[18:19], off offset:-2624
	v_add_u32_e32 v16, s8, v44
	v_mad_u64_u32 v[18:19], s[10:11], v16, s4, v[8:9]
	v_mov_b32_e32 v17, v45
	v_add_co_u32_e32 v20, vcc, s5, v18
	v_lshlrev_b64 v[24:25], 12, v[16:17]
	s_nop 0
	v_addc_co_u32_e32 v21, vcc, 0, v19, vcc
	v_lshlrev_b64 v[16:17], 11, v[16:17]
	v_add_co_u32_e32 v22, vcc, s12, v18
	v_lshl_add_u64 v[16:17], v[14:15], 0, v[16:17]
	s_nop 0
	v_addc_co_u32_e32 v23, vcc, -1, v19, vcc
	v_lshl_add_u64 v[24:25], v[12:13], 0, v[24:25]
	global_load_dword v133, v[18:19], off
	global_load_dword v126, v[18:19], off offset:2048
	global_load_dword v134, v[20:21], off
	global_load_dword v127, v[22:23], off offset:-2624
	global_load_dword v130, v[22:23], off offset:-576
	global_load_dwordx2 v[74:75], v[24:25], off
	global_load_dword v132, v[16:17], off
	global_load_dword v131, v[18:19], off offset:-2624
	v_add_u32_e32 v16, s8, v10
	v_mad_u64_u32 v[8:9], s[8:9], v16, s4, v[8:9]
	v_add_co_u32_e32 v18, vcc, s5, v8
	v_mov_b32_e32 v17, v45
	s_nop 0
	v_addc_co_u32_e32 v19, vcc, 0, v9, vcc
	v_add_co_u32_e32 v20, vcc, s12, v8
	v_lshlrev_b64 v[22:23], 12, v[16:17]
	v_lshlrev_b64 v[16:17], 11, v[16:17]
	v_addc_co_u32_e32 v21, vcc, -1, v9, vcc
	v_lshl_add_u64 v[12:13], v[12:13], 0, v[22:23]
	v_lshl_add_u64 v[14:15], v[14:15], 0, v[16:17]
	global_load_dword v140, v[8:9], off
	global_load_dword v136, v[8:9], off offset:2048
	global_load_dword v141, v[18:19], off
	global_load_dword v137, v[20:21], off offset:-2624
	global_load_dword v138, v[20:21], off offset:-576
	global_load_dwordx2 v[88:89], v[12:13], off
	global_load_dword v142, v[14:15], off
	global_load_dword v139, v[8:9], off offset:-2624
	s_mul_i32 s5, s27, 0x2100
	s_add_i32 s5, s5, 0
	s_add_i32 s5, s5, 0xfc00
	s_add_u32 s10, s94, 0x4700000
	s_addc_u32 s11, s95, 0
	s_add_u32 s12, s94, 0x2700000
	s_addc_u32 s13, s95, 0
	s_add_u32 s8, s94, 0x1f00000
	s_addc_u32 s9, s95, 0
	s_lshl_b32 s6, s24, 24
	v_lshlrev_b64 v[12:13], 12, v[2:3]
	v_and_b32_e32 v5, 7, v166
	v_lshl_add_u64 v[12:13], s[6:7], 0, v[12:13]
	v_lshl_add_u32 v117, v5, 4, s5
	v_lshlrev_b32_e32 v46, 3, v5
	v_mul_u32_u24_e32 v5, 0x420, v5
	v_lshlrev_b32_e32 v8, 2, v111
	v_lshl_add_u64 v[12:13], v[12:13], 0, v[0:1]
	v_add3_u32 v106, s5, v5, v8
	v_lshlrev_b32_e32 v5, 2, v166
	v_lshl_add_u64 v[52:53], v[12:13], 0, s[14:15]
	v_lshlrev_b64 v[12:13], 11, v[2:3]
	v_mul_hi_i32_i24_e32 v3, 0x1a40, v2
	v_mul_i32_i24_e32 v2, 0x1a40, v2
	v_mov_b32_e32 v9, 0x1a40000
	v_and_b32_e32 v8, 28, v5
	v_mov_b32_e32 v5, v45
	v_mad_u64_u32 v[2:3], s[20:21], s24, v9, v[2:3]
	v_lshl_add_u64 v[56:57], v[2:3], 0, v[4:5]
	v_lshlrev_b64 v[2:3], 12, v[6:7]
	v_lshl_add_u64 v[2:3], s[6:7], 0, v[2:3]
	v_lshl_add_u64 v[2:3], v[2:3], 0, v[0:1]
	v_lshl_add_u64 v[58:59], v[2:3], 0, s[14:15]
	v_lshlrev_b64 v[2:3], 11, v[6:7]
	v_mad_u64_u32 v[6:7], s[20:21], v6, s4, 0
	v_mad_u64_u32 v[14:15], s[20:21], v44, s4, 0
	v_mov_b32_e32 v11, v45
	v_mad_u64_u32 v[6:7], s[20:21], s24, v9, v[6:7]
	v_mad_u64_u32 v[14:15], s[20:21], s24, v9, v[14:15]
	v_lshl_add_u64 v[62:63], v[6:7], 0, v[4:5]
	v_lshlrev_b64 v[6:7], 12, v[44:45]
	v_lshl_add_u64 v[68:69], v[14:15], 0, v[4:5]
	v_lshlrev_b64 v[14:15], 12, v[10:11]
	v_lshl_add_u64 v[6:7], s[6:7], 0, v[6:7]
	v_lshl_add_u64 v[14:15], s[6:7], 0, v[14:15]
	v_lshl_add_u64 v[6:7], v[6:7], 0, v[0:1]
	v_lshl_add_u64 v[0:1], v[14:15], 0, v[0:1]
	s_lshl_b32 s16, s24, 23
	v_lshl_add_u64 v[70:71], v[0:1], 0, s[14:15]
	v_lshlrev_b64 v[0:1], 11, v[10:11]
	v_lshl_add_u64 v[64:65], v[6:7], 0, s[14:15]
	v_lshlrev_b64 v[6:7], 11, v[44:45]
	v_lshl_add_u64 v[0:1], s[16:17], 0, v[0:1]
	v_lshl_add_u64 v[6:7], s[16:17], 0, v[6:7]
	v_lshl_add_u64 v[0:1], v[0:1], 0, v[4:5]
	v_lshl_add_u64 v[12:13], s[16:17], 0, v[12:13]
	v_lshl_add_u64 v[2:3], s[16:17], 0, v[2:3]
	v_lshl_add_u64 v[6:7], v[6:7], 0, v[4:5]
	v_lshl_add_u64 v[72:73], v[0:1], 0, s[18:19]
	v_mad_u64_u32 v[10:11], s[4:5], v10, s4, 0
	s_mov_b64 s[14:15], 0x10000
	v_lshl_add_u64 v[0:1], s[92:93], 0, v[0:1]
	v_lshl_add_u64 v[12:13], v[12:13], 0, v[4:5]
	v_lshl_add_u64 v[2:3], v[2:3], 0, v[4:5]
	v_mad_u64_u32 v[10:11], s[4:5], s24, v9, v[10:11]
	v_lshl_add_u64 v[80:81], v[0:1], 0, s[14:15]
	v_lshl_add_u64 v[0:1], s[92:93], 0, v[6:7]
	v_lshl_add_u64 v[76:77], v[10:11], 0, v[4:5]
	v_lshl_add_u64 v[4:5], s[92:93], 0, v[12:13]
	v_lshl_add_u64 v[82:83], v[0:1], 0, s[14:15]
	v_lshl_add_u64 v[0:1], s[92:93], 0, v[2:3]
	v_add_u32_e32 v108, 0x3000, v104
	v_add_u32_e32 v109, 0x6000, v104
	v_add_u32_e32 v110, 0x9000, v104
	s_mov_b32 s41, -1
	s_mov_b32 s29, 1
	v_mul_u32_u24_e32 v118, 0x84, v111
	v_or_b32_e32 v107, 8, v111
	v_or_b32_e32 v105, 16, v111
	s_waitcnt lgkmcnt(3)
	v_or_b32_e32 v47, 24, v111
	v_lshl_add_u64 v[54:55], v[12:13], 0, s[18:19]
	v_lshl_add_u64 v[60:61], v[2:3], 0, s[18:19]
	v_lshl_add_u64 v[66:67], v[6:7], 0, s[18:19]
	v_lshl_add_u64 v[78:79], v[4:5], 0, s[14:15]
	v_lshl_add_u64 v[84:85], v[0:1], 0, s[14:15]
	s_mov_b64 s[16:17], 0
	s_movk_i32 s6, 0x7fff
	s_mov_b32 s31, 0xffff0000
	v_lshlrev_b32_e32 v86, 2, v8
	s_mov_b32 s34, 0x8b69000
	s_mov_b32 s35, 0x8b6a000
	s_mov_b32 s38, 0x8b67000
	s_mov_b32 s39, 0x8b68000
	s_mov_b64 s[18:19], 0x20000
	s_mov_b64 s[20:21], 0x34800
	v_mov_b32_e32 v135, 1
	s_mov_b32 s40, s30
	v_mov_b32_e32 v0, v45
	v_mov_b32_e32 v1, v45
	v_mov_b32_e32 v2, v45
	v_mov_b32_e32 v3, v45
	v_mov_b32_e32 v4, v45
	v_mov_b32_e32 v5, v45
	v_mov_b32_e32 v6, v45
	v_mov_b32_e32 v7, v45
	v_mov_b32_e32 v8, v45
	v_mov_b32_e32 v9, v45
	v_mov_b32_e32 v10, v45
	v_mov_b32_e32 v11, v45
	v_mov_b32_e32 v12, v45
	v_mov_b32_e32 v13, v45
	v_mov_b32_e32 v14, v45
	v_mov_b32_e32 v15, v45
	v_mov_b32_e32 v16, v45
	v_mov_b32_e32 v17, v45
	v_mov_b32_e32 v18, v45
	v_mov_b32_e32 v19, v45
	v_mov_b32_e32 v20, v45
	v_mov_b32_e32 v21, v45
	v_mov_b32_e32 v22, v45
	v_mov_b32_e32 v23, v45
	v_mov_b32_e32 v24, v45
	v_mov_b32_e32 v25, v45
	v_mov_b32_e32 v26, v45
	v_mov_b32_e32 v27, v45
	v_mov_b32_e32 v28, v45
	v_mov_b32_e32 v29, v45
	v_mov_b32_e32 v30, v45
	v_mov_b32_e32 v31, v45
	s_waitcnt vmcnt(31)
	v_lshl_add_u64 v[210:211], s[94:95], 0, v[56:57]
	v_lshl_add_u64 v[218:219], s[94:95], 0, v[52:53]
	v_add_co_u32_e32 v212, vcc, s34, v210
	v_lshl_add_u64 v[220:221], s[94:95], 0, v[54:55]
	s_nop 0
	v_addc_co_u32_e32 v213, vcc, 0, v211, vcc
	v_add_co_u32_e32 v214, vcc, s35, v210
	s_nop 1
	v_addc_co_u32_e32 v215, vcc, 0, v211, vcc
	v_add_co_u32_e32 v216, vcc, s39, v210
	s_nop 1
	v_addc_co_u32_e32 v217, vcc, 0, v211, vcc
	global_load_dword v170, v[212:213], off
	global_load_dword v171, v[212:213], off offset:2048
	global_load_dword v172, v[214:215], off
	global_load_dword v173, v[216:217], off offset:-2624
	global_load_dword v174, v[216:217], off offset:-576
	global_load_dword v177, v[212:213], off offset:-2624
	global_load_dwordx2 v[202:203], v[218:219], off
	global_load_dword v178, v[220:221], off
	v_lshl_add_u64 v[210:211], s[94:95], 0, v[62:63]
	v_lshl_add_u64 v[218:219], s[94:95], 0, v[58:59]
	v_add_co_u32_e32 v212, vcc, s34, v210
	v_lshl_add_u64 v[220:221], s[94:95], 0, v[60:61]
	s_nop 0
	v_addc_co_u32_e32 v213, vcc, 0, v211, vcc
	v_add_co_u32_e32 v214, vcc, s35, v210
	s_nop 1
	v_addc_co_u32_e32 v215, vcc, 0, v211, vcc
	v_add_co_u32_e32 v216, vcc, s39, v210
	s_nop 1
	v_addc_co_u32_e32 v217, vcc, 0, v211, vcc
	global_load_dword v186, v[212:213], off
	global_load_dword v179, v[212:213], off offset:2048
	global_load_dword v187, v[214:215], off
	global_load_dword v180, v[216:217], off offset:-2624
	global_load_dword v181, v[216:217], off offset:-576
	global_load_dword v182, v[212:213], off offset:-2624
	global_load_dwordx2 v[204:205], v[218:219], off
	global_load_dword v183, v[220:221], off
	v_lshl_add_u64 v[210:211], s[94:95], 0, v[68:69]
	v_lshl_add_u64 v[218:219], s[94:95], 0, v[64:65]
	v_add_co_u32_e32 v212, vcc, s34, v210
	v_lshl_add_u64 v[220:221], s[94:95], 0, v[66:67]
	s_nop 0
	v_addc_co_u32_e32 v213, vcc, 0, v211, vcc
	v_add_co_u32_e32 v214, vcc, s35, v210
	s_nop 1
	v_addc_co_u32_e32 v215, vcc, 0, v211, vcc
	v_add_co_u32_e32 v216, vcc, s39, v210
	s_nop 1
	v_addc_co_u32_e32 v217, vcc, 0, v211, vcc
	global_load_dword v191, v[212:213], off
	global_load_dword v184, v[212:213], off offset:2048
	global_load_dword v192, v[214:215], off
	global_load_dword v185, v[216:217], off offset:-2624
	global_load_dword v188, v[216:217], off offset:-576
	global_load_dword v189, v[212:213], off offset:-2624
	global_load_dwordx2 v[206:207], v[218:219], off
	global_load_dword v190, v[220:221], off
	v_lshl_add_u64 v[210:211], s[94:95], 0, v[76:77]
	v_lshl_add_u64 v[218:219], s[94:95], 0, v[70:71]
	v_add_co_u32_e32 v212, vcc, s34, v210
	v_lshl_add_u64 v[220:221], s[94:95], 0, v[72:73]
	s_nop 0
	v_addc_co_u32_e32 v213, vcc, 0, v211, vcc
	v_add_co_u32_e32 v214, vcc, s35, v210
	s_nop 1
	v_addc_co_u32_e32 v215, vcc, 0, v211, vcc
	v_add_co_u32_e32 v216, vcc, s39, v210
	s_nop 1
	v_addc_co_u32_e32 v217, vcc, 0, v211, vcc
	global_load_dword v198, v[212:213], off
	global_load_dword v194, v[212:213], off offset:2048
	global_load_dword v199, v[214:215], off
	global_load_dword v195, v[216:217], off offset:-2624
	global_load_dword v196, v[216:217], off offset:-576
	global_load_dword v197, v[212:213], off offset:-2624
	global_load_dwordx2 v[208:209], v[218:219], off
	global_load_dword v200, v[220:221], off
	v_lshl_add_u64 v[52:53], v[52:53], 0, s[18:19]
	v_lshl_add_u64 v[54:55], v[54:55], 0, s[14:15]
	v_lshl_add_u64 v[56:57], v[56:57], 0, s[20:21]
	v_lshl_add_u64 v[58:59], v[58:59], 0, s[18:19]
	v_lshl_add_u64 v[60:61], v[60:61], 0, s[14:15]
	v_lshl_add_u64 v[62:63], v[62:63], 0, s[20:21]
	v_lshl_add_u64 v[64:65], v[64:65], 0, s[18:19]
	v_lshl_add_u64 v[66:67], v[66:67], 0, s[14:15]
	v_lshl_add_u64 v[68:69], v[68:69], 0, s[20:21]
	v_lshl_add_u64 v[70:71], v[70:71], 0, s[18:19]
	v_lshl_add_u64 v[72:73], v[72:73], 0, s[14:15]
	v_lshl_add_u64 v[76:77], v[76:77], 0, s[20:21]
	s_waitcnt vmcnt(32)
	s_waitcnt lgkmcnt(0)
	s_barrier
	s_branch .LBB0_952

.LBB0_961:
	v_add_u32_e32 v44, v117, v118
	v_add_u32_e32 v87, 0x420, v44
	s_waitcnt vmcnt(43)
	ds_write2_b32 v44, v0, v1 offset1:1
	ds_write2_b32 v44, v2, v3 offset0:2 offset1:3
	s_waitcnt vmcnt(42)
	ds_write2_b32 v87, v4, v5 offset1:1
	v_add_u32_e32 v87, 0x428, v44
	ds_write2_b32 v87, v6, v7 offset1:1
	v_add_u32_e32 v87, 0x840, v44
	s_waitcnt vmcnt(41)
	ds_write2_b32 v87, v8, v9 offset1:1
	v_add_u32_e32 v87, 0x848, v44
	ds_write2_b32 v87, v10, v11 offset1:1
	v_add_u32_e32 v87, 0xc60, v44
	s_waitcnt vmcnt(40)
	ds_write2_b32 v87, v12, v13 offset1:1
	v_add_u32_e32 v87, 0xc68, v44
	ds_write2_b32 v87, v14, v15 offset1:1
	v_add_u32_e32 v87, 0x1080, v44
	s_waitcnt vmcnt(39)
	ds_write2_b32 v87, v16, v17 offset1:1
	v_add_u32_e32 v87, 0x1088, v44
	ds_write2_b32 v87, v18, v19 offset1:1
	v_add_u32_e32 v87, 0x14a0, v44
	s_waitcnt vmcnt(38)
	ds_write2_b32 v87, v20, v21 offset1:1
	v_add_u32_e32 v87, 0x14a8, v44
	ds_write2_b32 v87, v22, v23 offset1:1
	v_add_u32_e32 v87, 0x18c0, v44
	s_waitcnt vmcnt(37)
	ds_write2_b32 v87, v24, v25 offset1:1
	v_add_u32_e32 v87, 0x18c8, v44
	s_ff1_i32_b32 s5, s43
	ds_write2_b32 v87, v26, v27 offset1:1
	v_add_u32_e32 v87, 0x1ce0, v44
	v_add_u32_e32 v44, 0x1ce8, v44
	s_lshr_b32 s5, s41, s5
	s_waitcnt vmcnt(36)
	ds_write2_b32 v87, v28, v29 offset1:1
	ds_write2_b32 v44, v30, v31 offset1:1
	s_and_b32 s5, s5, 0xffff
	s_waitcnt lgkmcnt(0)
	s_mul_i32 s42, s43, s5
	ds_read2_b32 v[94:95], v106 offset1:8
	s_sub_i32 s41, s41, s42
	ds_read2_b32 v[98:99], v106 offset0:33 offset1:41
	s_lshl_b32 s41, s41, 5
	s_lshl_b32 s5, s5, 7
	s_add_u32 s22, s22, s5
	ds_read2_b32 v[144:145], v106 offset0:66 offset1:74
	s_addc_u32 s23, s23, 0
	v_lshlrev_b32_e32 v44, 1, v46
	ds_read2_b32 v[146:147], v106 offset0:99 offset1:107
	v_lshl_add_u64 v[96:97], s[22:23], 0, v[44:45]
	s_waitcnt lgkmcnt(3)
	v_bfe_u32 v44, v94, 16, 1
	v_add3_u32 v44, v94, v44, s6
	s_waitcnt lgkmcnt(2)
	v_bfe_u32 v87, v98, 16, 1
	ds_read2_b32 v[148:149], v106 offset0:132 offset1:140
	v_lshrrev_b32_e32 v44, 16, v44
	v_add3_u32 v87, v98, v87, s6
	ds_read2_b32 v[150:151], v106 offset0:165 offset1:173
	v_and_or_b32 v90, v87, s31, v44
	s_waitcnt lgkmcnt(3)
	v_bfe_u32 v44, v144, 16, 1
	v_add3_u32 v44, v144, v44, s6
	s_waitcnt lgkmcnt(2)
	v_bfe_u32 v87, v146, 16, 1
	ds_read2_b32 v[152:153], v106 offset0:198 offset1:206
	v_lshrrev_b32_e32 v44, 16, v44
	v_add3_u32 v87, v146, v87, s6
	ds_read2_b32 v[154:155], v106 offset0:231 offset1:239
	v_and_or_b32 v91, v87, s31, v44
	s_waitcnt lgkmcnt(3)
	v_bfe_u32 v44, v148, 16, 1
	v_add3_u32 v44, v148, v44, s6
	s_waitcnt lgkmcnt(2)
	v_bfe_u32 v87, v150, 16, 1
	v_lshrrev_b32_e32 v44, 16, v44
	v_add3_u32 v87, v150, v87, s6
	v_and_or_b32 v92, v87, s31, v44
	s_waitcnt lgkmcnt(1)
	v_bfe_u32 v44, v152, 16, 1
	v_add3_u32 v44, v152, v44, s6
	s_waitcnt lgkmcnt(0)
	v_bfe_u32 v87, v154, 16, 1
	v_lshrrev_b32_e32 v44, 16, v44
	v_add3_u32 v87, v154, v87, s6
	v_and_or_b32 v93, v87, s31, v44
	v_or_b32_e32 v44, s41, v111
	v_mad_i64_i32 v[156:157], s[22:23], s4, v44, 0
	v_bfe_u32 v44, v95, 16, 1
	v_add3_u32 v44, v95, v44, s6
	v_bfe_u32 v87, v99, 16, 1
	v_lshl_add_u64 v[156:157], v[156:157], 1, v[96:97]
	v_lshrrev_b32_e32 v44, 16, v44
	v_add3_u32 v87, v99, v87, s6
	global_store_dwordx4 v[156:157], v[90:93], off
	ds_read2_b32 v[94:95], v106 offset0:16 offset1:24
	s_nop 0
	v_and_or_b32 v90, v87, s31, v44
	v_bfe_u32 v44, v145, 16, 1
	v_add3_u32 v44, v145, v44, s6
	v_bfe_u32 v87, v147, 16, 1
	v_lshrrev_b32_e32 v44, 16, v44
	v_add3_u32 v87, v147, v87, s6
	v_and_or_b32 v91, v87, s31, v44
	v_bfe_u32 v44, v149, 16, 1
	v_add3_u32 v44, v149, v44, s6
	v_bfe_u32 v87, v151, 16, 1
	v_lshrrev_b32_e32 v44, 16, v44
	v_add3_u32 v87, v151, v87, s6
	v_and_or_b32 v92, v87, s31, v44
	v_bfe_u32 v44, v153, 16, 1
	v_add3_u32 v44, v153, v44, s6
	v_bfe_u32 v87, v155, 16, 1
	v_lshrrev_b32_e32 v44, 16, v44
	v_add3_u32 v87, v155, v87, s6
	v_and_or_b32 v93, v87, s31, v44
	v_or_b32_e32 v44, s41, v107
	v_mad_i64_i32 v[98:99], s[22:23], s4, v44, 0
	v_lshl_add_u64 v[98:99], v[98:99], 1, v[96:97]
	global_store_dwordx4 v[98:99], v[90:93], off
	ds_read2_b32 v[98:99], v106 offset0:49 offset1:57
	ds_read2_b32 v[144:145], v106 offset0:82 offset1:90
	ds_read2_b32 v[146:147], v106 offset0:115 offset1:123
	s_waitcnt lgkmcnt(3)
	v_bfe_u32 v44, v94, 16, 1
	v_add3_u32 v44, v94, v44, s6
	s_waitcnt lgkmcnt(2)
	v_bfe_u32 v87, v98, 16, 1
	ds_read2_b32 v[148:149], v106 offset0:148 offset1:156
	v_lshrrev_b32_e32 v44, 16, v44
	v_add3_u32 v87, v98, v87, s6
	ds_read2_b32 v[150:151], v106 offset0:181 offset1:189
	v_and_or_b32 v90, v87, s31, v44
	s_waitcnt lgkmcnt(3)
	v_bfe_u32 v44, v144, 16, 1
	v_add3_u32 v44, v144, v44, s6
	s_waitcnt lgkmcnt(2)
	v_bfe_u32 v87, v146, 16, 1
	ds_read2_b32 v[152:153], v106 offset0:214 offset1:222
	v_lshrrev_b32_e32 v44, 16, v44
	v_add3_u32 v87, v146, v87, s6
	ds_read2_b32 v[154:155], v106 offset0:247 offset1:255
	v_and_or_b32 v91, v87, s31, v44
	s_waitcnt lgkmcnt(3)
	v_bfe_u32 v44, v148, 16, 1
	v_add3_u32 v44, v148, v44, s6
	s_waitcnt lgkmcnt(2)
	v_bfe_u32 v87, v150, 16, 1
	v_lshrrev_b32_e32 v44, 16, v44
	v_add3_u32 v87, v150, v87, s6
	v_and_or_b32 v92, v87, s31, v44
	s_waitcnt lgkmcnt(1)
	v_bfe_u32 v44, v152, 16, 1
	v_add3_u32 v44, v152, v44, s6
	s_waitcnt lgkmcnt(0)
	v_bfe_u32 v87, v154, 16, 1
	v_lshrrev_b32_e32 v44, 16, v44
	v_add3_u32 v87, v154, v87, s6
	v_and_or_b32 v93, v87, s31, v44
	v_or_b32_e32 v44, s41, v105
	v_mad_i64_i32 v[156:157], s[22:23], s4, v44, 0
	v_bfe_u32 v44, v95, 16, 1
	v_add3_u32 v44, v95, v44, s6
	v_bfe_u32 v87, v99, 16, 1
	v_lshl_add_u64 v[156:157], v[156:157], 1, v[96:97]
	v_lshrrev_b32_e32 v44, 16, v44
	v_add3_u32 v87, v99, v87, s6
	global_store_dwordx4 v[156:157], v[90:93], off
	s_nop 1
	v_and_or_b32 v90, v87, s31, v44
	v_bfe_u32 v44, v145, 16, 1
	v_add3_u32 v44, v145, v44, s6
	v_bfe_u32 v87, v147, 16, 1
	v_lshrrev_b32_e32 v44, 16, v44
	v_add3_u32 v87, v147, v87, s6
	v_and_or_b32 v91, v87, s31, v44
	v_bfe_u32 v44, v149, 16, 1
	v_add3_u32 v44, v149, v44, s6
	v_bfe_u32 v87, v151, 16, 1
	v_lshrrev_b32_e32 v44, 16, v44
	v_add3_u32 v87, v151, v87, s6
	v_and_or_b32 v92, v87, s31, v44
	v_bfe_u32 v44, v153, 16, 1
	v_add3_u32 v44, v153, v44, s6
	v_bfe_u32 v87, v155, 16, 1
	v_lshrrev_b32_e32 v44, 16, v44
	v_add3_u32 v87, v155, v87, s6
	v_and_or_b32 v93, v87, s31, v44
	v_or_b32_e32 v44, s41, v47
	v_mad_i64_i32 v[94:95], s[4:5], s4, v44, 0
	v_lshl_add_u64 v[94:95], v[94:95], 1, v[96:97]
	global_store_dwordx4 v[94:95], v[90:93], off
	s_waitcnt lgkmcnt(0)

.LBB0_970:
	s_lshr_b32 s23, s22, 5
	s_nop 0
	v_cvt_f32_u32_e32 v0, s23
	s_sub_i32 s44, 0, s23
	s_abs_i32 s43, s41
	s_ashr_i32 s42, s41, 31
	v_rcp_iflag_f32_e32 v0, v0
	v_mov_b32_e32 v87, v45
	v_mul_f32_e32 v0, 0x4f7ffffe, v0
	v_cvt_u32_f32_e32 v0, v0
	s_nop 0
	v_readfirstlane_b32 s45, v0
	s_mul_i32 s44, s44, s45
	s_mul_hi_u32 s44, s45, s44
	s_add_i32 s45, s45, s44
	s_mul_hi_u32 s44, s43, s45
	s_mul_i32 s45, s44, s23
	s_sub_i32 s43, s43, s45
	s_add_i32 s46, s44, 1
	s_sub_i32 s45, s43, s23
	s_cmp_ge_u32 s43, s23
	s_cselect_b32 s44, s46, s44
	s_cselect_b32 s43, s45, s43
	s_add_i32 s45, s44, 1
	s_cmp_ge_u32 s43, s23
	s_cselect_b32 s43, s45, s44
	s_xor_b32 s43, s43, s42
	s_sub_i32 s42, s43, s42
	s_mul_i32 s23, s42, s23
	s_nop 0
	v_lshl_or_b32 v28, s42, 6, v111
	s_sub_i32 s23, s41, s23
	v_mad_i64_i32 v[0:1], s[42:43], v28, s22, 0
	s_lshl_b32 s42, s23, 5
	s_ashr_i32 s43, s42, 31
	s_lshl_b64 s[42:43], s[42:43], 2
	s_add_u32 s4, s4, s42
	s_addc_u32 s5, s5, s43
	v_or_b32_e32 v2, 8, v28
	v_or_b32_e32 v8, 16, v28
	v_or_b32_e32 v10, 24, v28
	v_or_b32_e32 v16, 32, v28
	v_or_b32_e32 v18, 40, v28
	v_or_b32_e32 v26, 48, v28
	v_or_b32_e32 v28, 56, v28
	v_lshl_add_u64 v[24:25], s[4:5], 0, v[86:87]
	v_mad_i64_i32 v[2:3], s[4:5], v2, s22, 0
	v_mad_i64_i32 v[8:9], s[4:5], v8, s22, 0
	v_mad_i64_i32 v[10:11], s[4:5], v10, s22, 0
	v_mad_i64_i32 v[16:17], s[4:5], v16, s22, 0
	v_mad_i64_i32 v[18:19], s[4:5], v18, s22, 0
	v_mad_i64_i32 v[26:27], s[4:5], v26, s22, 0
	v_mad_i64_i32 v[28:29], s[4:5], v28, s22, 0
	v_lshl_add_u64 v[0:1], v[0:1], 2, v[24:25]
	v_lshl_add_u64 v[4:5], v[2:3], 2, v[24:25]
	v_lshl_add_u64 v[8:9], v[8:9], 2, v[24:25]
	v_lshl_add_u64 v[12:13], v[10:11], 2, v[24:25]
	v_lshl_add_u64 v[16:17], v[16:17], 2, v[24:25]
	v_lshl_add_u64 v[20:21], v[18:19], 2, v[24:25]
	v_lshl_add_u64 v[26:27], v[26:27], 2, v[24:25]
	v_lshl_add_u64 v[28:29], v[28:29], 2, v[24:25]
	global_load_dwordx4 v[0:3], v[0:1], off
	s_nop 0
	global_load_dwordx4 v[4:7], v[4:5], off
	s_nop 0
	global_load_dwordx4 v[8:11], v[8:9], off
	s_nop 0
	global_load_dwordx4 v[12:15], v[12:13], off
	s_nop 0
	global_load_dwordx4 v[16:19], v[16:17], off
	s_nop 0
	global_load_dwordx4 v[20:23], v[20:21], off
	s_nop 0
	global_load_dwordx4 v[24:27], v[26:27], off
	s_nop 0
	global_load_dwordx4 v[28:31], v[28:29], off
	s_mov_b32 s41, s40
.LBB0_971:
	s_cmp_eq_u32 s16, 0x7f0000
	s_cbranch_scc1 .LBB0_951
	s_nop 0
	v_lshlrev_b32_e32 v94, 16, v113
	v_and_b32_e32 v95, 0xffff0000, v113
	s_nop 0
	v_lshlrev_b32_e32 v96, 16, v116
	v_and_b32_e32 v97, 0xffff0000, v116
	v_pk_add_f32 v[96:97], v[96:97], v[94:95] neg_lo:[0,1] neg_hi:[0,1]
	v_lshlrev_b32_e32 v90, 16, v112
	v_and_b32_e32 v91, 0xffff0000, v112
	v_lshlrev_b32_e32 v92, 16, v115
	v_and_b32_e32 v93, 0xffff0000, v115
	v_pk_fma_f32 v[96:97], v[38:39], v[96:97], v[94:95]
	v_pk_add_f32 v[92:93], v[92:93], v[90:91] neg_lo:[0,1] neg_hi:[0,1]
	v_pk_mul_f32 v[94:95], v[36:37], v[96:97]
	v_pk_fma_f32 v[90:91], v[32:33], v[92:93], v[90:91]
	s_nop 0
	v_lshlrev_b32_e32 v92, 16, v120
	v_and_b32_e32 v93, 0xffff0000, v120
	v_pk_mul_f32 v[144:145], v[94:95], v[94:95]
	v_lshlrev_b32_e32 v98, 16, v114
	v_add_f32_e32 v44, v144, v145
	v_pk_add_f32 v[144:145], v[92:93], -1.0 op_sel_hi:[1,0]
	v_and_b32_e32 v99, 0xffff0000, v114
	v_pk_fma_f32 v[144:145], v[40:41], v[144:145], 1.0 op_sel_hi:[1,1,0]
	v_add_f32_dpp v44, v44, v44 quad_perm:[1,0,3,2] row_mask:0xf bank_mask:0xf bound_ctrl:1
	v_pk_mul_f32 v[96:97], v[96:97], v[144:145]
	s_nop 0
	v_lshlrev_b32_e32 v146, 16, v119
	v_pk_mul_f32 v[144:145], v[90:91], v[96:97]
	v_add_f32_dpp v44, v44, v44 quad_perm:[2,3,0,1] row_mask:0xf bank_mask:0xf bound_ctrl:1
	v_mul_f32_e32 v143, v43, v145
	v_fmac_f32_e32 v143, v42, v144
	v_add_f32_dpp v44, v44, v44 row_half_mirror row_mask:0xf bank_mask:0xf bound_ctrl:1
	v_and_b32_e32 v147, 0xffff0000, v119
	v_add_f32_dpp v143, v143, v143 quad_perm:[1,0,3,2] row_mask:0xf bank_mask:0xf bound_ctrl:1
	v_add_f32_dpp v44, v44, v44 row_mirror row_mask:0xf bank_mask:0xf bound_ctrl:1
	ds_bpermute_b32 v87, v102, v44
	v_add_f32_dpp v143, v143, v143 quad_perm:[2,3,0,1] row_mask:0xf bank_mask:0xf bound_ctrl:1
	v_pk_add_f32 v[146:147], v[146:147], v[98:99] neg_lo:[0,1] neg_hi:[0,1]
	s_nop 0
	v_add_f32_dpp v143, v143, v143 row_half_mirror row_mask:0xf bank_mask:0xf bound_ctrl:1
	v_pk_fma_f32 v[98:99], v[34:35], v[146:147], v[98:99]
	s_nop 0
	v_add_f32_dpp v143, v143, v143 row_mirror row_mask:0xf bank_mask:0xf bound_ctrl:1
	ds_bpermute_b32 v144, v102, v143
	s_and_saveexec_b64 s[4:5], s[0:1]
	s_cbranch_execz .LBB0_974
	s_waitcnt lgkmcnt(0)
	v_add_f32_e32 v144, v143, v144
	v_pk_mul_f32 v[144:145], v[98:99], v[144:145] op_sel_hi:[1,0]
	s_nop 0
	v_and_b32_sdwa v146, v144, v135 dst_sel:DWORD dst_unused:UNUSED_PAD src0_sel:WORD_1 src1_sel:DWORD
	v_and_b32_sdwa v143, v145, v135 dst_sel:DWORD dst_unused:UNUSED_PAD src0_sel:WORD_1 src1_sel:DWORD
	v_add3_u32 v144, v144, v146, s6
	v_add3_u32 v143, v145, v143, s6
	v_lshrrev_b32_e32 v144, 16, v144
	v_and_or_b32 v143, v143, s31, v144
	v_lshl_add_u64 v[144:145], v[78:79], 0, s[16:17]
	global_store_dword v[144:145], v143, off
.LBB0_974:
	s_or_b64 exec, exec, s[4:5]
	s_waitcnt lgkmcnt(1)
	v_add_f32_e32 v44, v44, v87
	v_mul_f32_e32 v87, 0x4f800000, v44
	v_cmp_gt_f32_e32 vcc, s28, v44
	s_bitcmp1_b32 s29, 0
	s_nop 0
	v_and_b32_e32 v147, 0xffff0000, v124
	v_cndmask_b32_e32 v44, v44, v87, vcc
	v_sqrt_f32_e32 v87, v44
	s_nop 0
	v_add_u32_e32 v143, -1, v87
	v_fma_f32 v145, -v143, v87, v44
	s_waitcnt lgkmcnt(0)
	v_add_u32_e32 v144, 1, v87
	v_cmp_ge_f32_e64 s[4:5], 0, v145
	s_nop 1
	v_cndmask_b32_e64 v143, v87, v143, s[4:5]
	v_fma_f32 v87, -v144, v87, v44
	v_cmp_lt_f32_e64 s[4:5], 0, v87
	s_nop 1
	v_cndmask_b32_e64 v87, v143, v144, s[4:5]
	v_mul_f32_e32 v143, 0x37800000, v87
	v_cndmask_b32_e32 v87, v87, v143, vcc
	v_cmp_class_f32_e32 vcc, v44, v103
	s_nop 1
	v_cndmask_b32_e32 v44, v87, v44, vcc
	v_max_f32_e32 v44, 0x2b8cbccc, v44
	v_div_scale_f32 v87, s[4:5], v44, v44, 1.0
	v_rcp_f32_e32 v143, v87
	s_cselect_b32 s4, 0xc000, 0
	s_add_i32 s22, s4, 0
	v_fma_f32 v144, -v87, v143, 1.0
	v_fmac_f32_e32 v143, v144, v143
	v_div_scale_f32 v144, vcc, 1.0, v44, 1.0
	v_mul_f32_e32 v145, v144, v143
	v_fma_f32 v146, -v87, v145, v144
	v_fmac_f32_e32 v145, v146, v143
	v_fma_f32 v87, -v87, v145, v144
	v_div_fmas_f32 v87, v87, v143, v145
	v_div_fixup_f32 v144, v87, v44, 1.0
	v_lshlrev_b32_e32 v44, 2, v101
	v_pk_mul_f32 v[94:95], v[94:95], v[144:145] op_sel_hi:[1,0] neg_lo:[0,1] neg_hi:[0,1]
	v_add3_u32 v87, s22, v104, v44
	v_pk_mul_f32 v[92:93], v[94:95], v[92:93] neg_lo:[1,0] neg_hi:[1,0]
	ds_write2_b64 v87, v[48:49], v[96:97] offset1:32
	ds_write2_b64 v87, v[94:95], v[92:93] offset0:64 offset1:96
	ds_write2_b64 v87, v[90:91], v[98:99] offset0:128 offset1:160
	v_lshlrev_b32_e32 v94, 16, v121
	v_and_b32_e32 v95, 0xffff0000, v121
	v_lshlrev_b32_e32 v96, 16, v123
	v_and_b32_e32 v97, 0xffff0000, v123
	v_pk_add_f32 v[96:97], v[96:97], v[94:95] neg_lo:[0,1] neg_hi:[0,1]
	s_nop 0
	v_lshlrev_b32_e32 v90, 16, v128
	v_and_b32_e32 v91, 0xffff0000, v128
	v_lshlrev_b32_e32 v92, 16, v122
	v_and_b32_e32 v93, 0xffff0000, v122
	v_pk_fma_f32 v[96:97], v[38:39], v[96:97], v[94:95]
	v_pk_add_f32 v[92:93], v[92:93], v[90:91] neg_lo:[0,1] neg_hi:[0,1]
	v_pk_mul_f32 v[94:95], v[36:37], v[96:97]
	v_pk_fma_f32 v[90:91], v[32:33], v[92:93], v[90:91]
	v_lshlrev_b32_e32 v92, 16, v125
	v_and_b32_e32 v93, 0xffff0000, v125
	v_pk_mul_f32 v[144:145], v[94:95], v[94:95]
	s_nop 0
	v_lshlrev_b32_e32 v98, 16, v129
	v_add_f32_e32 v87, v144, v145
	v_pk_add_f32 v[144:145], v[92:93], -1.0 op_sel_hi:[1,0]
	v_and_b32_e32 v99, 0xffff0000, v129
	v_pk_fma_f32 v[144:145], v[40:41], v[144:145], 1.0 op_sel_hi:[1,1,0]
	v_add_f32_dpp v87, v87, v87 quad_perm:[1,0,3,2] row_mask:0xf bank_mask:0xf bound_ctrl:1
	v_pk_mul_f32 v[96:97], v[96:97], v[144:145]
	v_lshlrev_b32_e32 v146, 16, v124
	v_pk_mul_f32 v[144:145], v[90:91], v[96:97]
	v_add_f32_dpp v87, v87, v87 quad_perm:[2,3,0,1] row_mask:0xf bank_mask:0xf bound_ctrl:1
	v_mul_f32_e32 v145, v43, v145
	v_fmac_f32_e32 v145, v42, v144
	v_add_f32_dpp v87, v87, v87 row_half_mirror row_mask:0xf bank_mask:0xf bound_ctrl:1
	v_pk_add_f32 v[146:147], v[146:147], v[98:99] neg_lo:[0,1] neg_hi:[0,1]
	v_add_f32_dpp v144, v145, v145 quad_perm:[1,0,3,2] row_mask:0xf bank_mask:0xf bound_ctrl:1
	v_add_f32_dpp v87, v87, v87 row_mirror row_mask:0xf bank_mask:0xf bound_ctrl:1
	ds_bpermute_b32 v143, v102, v87
	v_add_f32_dpp v144, v144, v144 quad_perm:[2,3,0,1] row_mask:0xf bank_mask:0xf bound_ctrl:1
	v_pk_fma_f32 v[98:99], v[34:35], v[146:147], v[98:99]
	s_nop 0
	v_add_f32_dpp v144, v144, v144 row_half_mirror row_mask:0xf bank_mask:0xf bound_ctrl:1
	s_nop 1
	v_add_f32_dpp v144, v144, v144 row_mirror row_mask:0xf bank_mask:0xf bound_ctrl:1
	ds_bpermute_b32 v145, v102, v144
	s_and_saveexec_b64 s[4:5], s[0:1]
	s_cbranch_execz .LBB0_976
	s_waitcnt lgkmcnt(0)
	v_add_f32_e32 v144, v144, v145
	v_pk_mul_f32 v[144:145], v[98:99], v[144:145] op_sel_hi:[1,0]
	s_nop 0
	v_and_b32_sdwa v147, v144, v135 dst_sel:DWORD dst_unused:UNUSED_PAD src0_sel:WORD_1 src1_sel:DWORD
	v_and_b32_sdwa v146, v145, v135 dst_sel:DWORD dst_unused:UNUSED_PAD src0_sel:WORD_1 src1_sel:DWORD
	v_add3_u32 v144, v144, v147, s6
	v_add3_u32 v145, v145, v146, s6
	v_lshrrev_b32_e32 v144, 16, v144
	v_and_or_b32 v146, v145, s31, v144
	v_lshl_add_u64 v[144:145], v[84:85], 0, s[16:17]
	global_store_dword v[144:145], v146, off
.LBB0_976:
	s_or_b64 exec, exec, s[4:5]
	s_waitcnt lgkmcnt(1)
	v_add_f32_e32 v87, v87, v143
	v_mul_f32_e32 v143, 0x4f800000, v87
	v_cmp_gt_f32_e32 vcc, s28, v87
	s_nop 1
	v_cndmask_b32_e32 v87, v87, v143, vcc
	v_sqrt_f32_e32 v143, v87
	s_nop 0
	v_add_u32_e32 v144, -1, v143
	v_fma_f32 v146, -v144, v143, v87
	s_waitcnt lgkmcnt(0)
	v_add_u32_e32 v145, 1, v143
	v_cmp_ge_f32_e64 s[4:5], 0, v146
	s_nop 1
	v_cndmask_b32_e64 v144, v143, v144, s[4:5]
	v_fma_f32 v143, -v145, v143, v87
	v_cmp_lt_f32_e64 s[4:5], 0, v143
	s_nop 1
	v_cndmask_b32_e64 v143, v144, v145, s[4:5]
	v_mul_f32_e32 v144, 0x37800000, v143
	v_cndmask_b32_e32 v143, v143, v144, vcc
	v_cmp_class_f32_e32 vcc, v87, v103
	s_nop 1
	v_cndmask_b32_e32 v87, v143, v87, vcc
	v_max_f32_e32 v87, 0x2b8cbccc, v87
	v_div_scale_f32 v143, s[4:5], v87, v87, 1.0
	v_rcp_f32_e32 v144, v143
	s_nop 0
	v_fma_f32 v145, -v143, v144, 1.0
	v_fmac_f32_e32 v144, v145, v144
	v_div_scale_f32 v145, vcc, 1.0, v87, 1.0
	v_mul_f32_e32 v146, v145, v144
	v_fma_f32 v147, -v143, v146, v145
	v_fmac_f32_e32 v146, v147, v144
	v_fma_f32 v143, -v143, v146, v145
	v_div_fmas_f32 v143, v143, v144, v146
	v_div_fixup_f32 v144, v143, v87, 1.0
	v_pk_mul_f32 v[94:95], v[94:95], v[144:145] op_sel_hi:[1,0] neg_lo:[0,1] neg_hi:[0,1]
	v_add3_u32 v87, s22, v108, v44
	v_pk_mul_f32 v[92:93], v[94:95], v[92:93] neg_lo:[1,0] neg_hi:[1,0]
	ds_write2_b64 v87, v[50:51], v[96:97] offset1:32
	ds_write2_b64 v87, v[94:95], v[92:93] offset0:64 offset1:96
	ds_write2_b64 v87, v[90:91], v[98:99] offset0:128 offset1:160
	s_nop 0
	v_lshlrev_b32_e32 v94, 16, v126
	v_and_b32_e32 v95, 0xffff0000, v126
	s_nop 0
	v_lshlrev_b32_e32 v96, 16, v130
	v_and_b32_e32 v97, 0xffff0000, v130
	v_pk_add_f32 v[96:97], v[96:97], v[94:95] neg_lo:[0,1] neg_hi:[0,1]
	s_nop 0
	v_lshlrev_b32_e32 v90, 16, v133
	v_and_b32_e32 v91, 0xffff0000, v133
	v_lshlrev_b32_e32 v92, 16, v127
	v_and_b32_e32 v93, 0xffff0000, v127
	v_pk_fma_f32 v[96:97], v[38:39], v[96:97], v[94:95]
	v_pk_add_f32 v[92:93], v[92:93], v[90:91] neg_lo:[0,1] neg_hi:[0,1]
	v_pk_mul_f32 v[94:95], v[36:37], v[96:97]
	v_pk_fma_f32 v[90:91], v[32:33], v[92:93], v[90:91]
	s_nop 0
	v_lshlrev_b32_e32 v92, 16, v132
	v_and_b32_e32 v93, 0xffff0000, v132
	v_pk_mul_f32 v[144:145], v[94:95], v[94:95]
	s_nop 0
	v_lshlrev_b32_e32 v98, 16, v134
	v_add_f32_e32 v87, v144, v145
	v_pk_add_f32 v[144:145], v[92:93], -1.0 op_sel_hi:[1,0]
	v_and_b32_e32 v99, 0xffff0000, v134
	v_pk_fma_f32 v[144:145], v[40:41], v[144:145], 1.0 op_sel_hi:[1,1,0]
	v_add_f32_dpp v87, v87, v87 quad_perm:[1,0,3,2] row_mask:0xf bank_mask:0xf bound_ctrl:1
	v_pk_mul_f32 v[96:97], v[96:97], v[144:145]
	s_nop 0
	v_lshlrev_b32_e32 v146, 16, v131
	v_pk_mul_f32 v[144:145], v[90:91], v[96:97]
	v_add_f32_dpp v87, v87, v87 quad_perm:[2,3,0,1] row_mask:0xf bank_mask:0xf bound_ctrl:1
	v_mul_f32_e32 v145, v43, v145
	v_fmac_f32_e32 v145, v42, v144
	v_add_f32_dpp v87, v87, v87 row_half_mirror row_mask:0xf bank_mask:0xf bound_ctrl:1
	v_and_b32_e32 v147, 0xffff0000, v131
	v_add_f32_dpp v144, v145, v145 quad_perm:[1,0,3,2] row_mask:0xf bank_mask:0xf bound_ctrl:1
	v_add_f32_dpp v87, v87, v87 row_mirror row_mask:0xf bank_mask:0xf bound_ctrl:1
	ds_bpermute_b32 v143, v102, v87
	v_add_f32_dpp v144, v144, v144 quad_perm:[2,3,0,1] row_mask:0xf bank_mask:0xf bound_ctrl:1
	v_pk_add_f32 v[146:147], v[146:147], v[98:99] neg_lo:[0,1] neg_hi:[0,1]
	s_nop 0
	v_add_f32_dpp v144, v144, v144 row_half_mirror row_mask:0xf bank_mask:0xf bound_ctrl:1
	v_pk_fma_f32 v[98:99], v[34:35], v[146:147], v[98:99]
	s_nop 0
	v_add_f32_dpp v144, v144, v144 row_mirror row_mask:0xf bank_mask:0xf bound_ctrl:1
	ds_bpermute_b32 v145, v102, v144
	s_and_saveexec_b64 s[4:5], s[0:1]
	s_cbranch_execz .LBB0_978
	s_waitcnt lgkmcnt(0)
	v_add_f32_e32 v144, v144, v145
	v_pk_mul_f32 v[144:145], v[98:99], v[144:145] op_sel_hi:[1,0]
	s_nop 0
	v_and_b32_sdwa v147, v144, v135 dst_sel:DWORD dst_unused:UNUSED_PAD src0_sel:WORD_1 src1_sel:DWORD
	v_and_b32_sdwa v146, v145, v135 dst_sel:DWORD dst_unused:UNUSED_PAD src0_sel:WORD_1 src1_sel:DWORD
	v_add3_u32 v144, v144, v147, s6
	v_add3_u32 v145, v145, v146, s6
	v_lshrrev_b32_e32 v144, 16, v144
	v_and_or_b32 v146, v145, s31, v144
	v_lshl_add_u64 v[144:145], v[82:83], 0, s[16:17]
	global_store_dword v[144:145], v146, off
.LBB0_978:
	s_or_b64 exec, exec, s[4:5]
	s_waitcnt lgkmcnt(1)
	v_add_f32_e32 v87, v87, v143
	v_mul_f32_e32 v143, 0x4f800000, v87
	v_cmp_gt_f32_e32 vcc, s28, v87
	s_nop 1
	v_cndmask_b32_e32 v87, v87, v143, vcc
	v_sqrt_f32_e32 v143, v87
	s_nop 0
	v_add_u32_e32 v144, -1, v143
	v_fma_f32 v146, -v144, v143, v87
	s_waitcnt lgkmcnt(0)
	v_add_u32_e32 v145, 1, v143
	v_cmp_ge_f32_e64 s[4:5], 0, v146
	s_nop 1
	v_cndmask_b32_e64 v144, v143, v144, s[4:5]
	v_fma_f32 v143, -v145, v143, v87
	v_cmp_lt_f32_e64 s[4:5], 0, v143
	s_nop 1
	v_cndmask_b32_e64 v143, v144, v145, s[4:5]
	v_mul_f32_e32 v144, 0x37800000, v143
	v_cndmask_b32_e32 v143, v143, v144, vcc
	v_cmp_class_f32_e32 vcc, v87, v103
	s_nop 1
	v_cndmask_b32_e32 v87, v143, v87, vcc
	v_max_f32_e32 v87, 0x2b8cbccc, v87
	v_div_scale_f32 v143, s[4:5], v87, v87, 1.0
	v_rcp_f32_e32 v144, v143
	s_nop 0
	v_fma_f32 v145, -v143, v144, 1.0
	v_fmac_f32_e32 v144, v145, v144
	v_div_scale_f32 v145, vcc, 1.0, v87, 1.0
	v_mul_f32_e32 v146, v145, v144
	v_fma_f32 v147, -v143, v146, v145
	v_fmac_f32_e32 v146, v147, v144
	v_fma_f32 v143, -v143, v146, v145
	v_div_fmas_f32 v143, v143, v144, v146
	v_div_fixup_f32 v144, v143, v87, 1.0
	v_pk_mul_f32 v[94:95], v[94:95], v[144:145] op_sel_hi:[1,0] neg_lo:[0,1] neg_hi:[0,1]
	v_add3_u32 v87, s22, v109, v44
	v_pk_mul_f32 v[92:93], v[94:95], v[92:93] neg_lo:[1,0] neg_hi:[1,0]
	ds_write2_b64 v87, v[74:75], v[96:97] offset1:32
	ds_write2_b64 v87, v[94:95], v[92:93] offset0:64 offset1:96
	ds_write2_b64 v87, v[90:91], v[98:99] offset0:128 offset1:160
	s_nop 0
	v_lshlrev_b32_e32 v94, 16, v136
	v_and_b32_e32 v95, 0xffff0000, v136
	s_nop 0
	v_lshlrev_b32_e32 v96, 16, v138
	v_and_b32_e32 v97, 0xffff0000, v138
	v_pk_add_f32 v[96:97], v[96:97], v[94:95] neg_lo:[0,1] neg_hi:[0,1]
	v_lshlrev_b32_e32 v90, 16, v140
	v_and_b32_e32 v91, 0xffff0000, v140
	v_lshlrev_b32_e32 v92, 16, v137
	v_and_b32_e32 v93, 0xffff0000, v137
	v_pk_fma_f32 v[96:97], v[38:39], v[96:97], v[94:95]
	v_pk_add_f32 v[92:93], v[92:93], v[90:91] neg_lo:[0,1] neg_hi:[0,1]
	v_pk_mul_f32 v[94:95], v[36:37], v[96:97]
	v_pk_fma_f32 v[90:91], v[32:33], v[92:93], v[90:91]
	s_nop 0
	v_lshlrev_b32_e32 v92, 16, v142
	v_and_b32_e32 v93, 0xffff0000, v142
	v_pk_mul_f32 v[144:145], v[94:95], v[94:95]
	v_lshlrev_b32_e32 v98, 16, v141
	v_add_f32_e32 v87, v144, v145
	v_pk_add_f32 v[144:145], v[92:93], -1.0 op_sel_hi:[1,0]
	v_and_b32_e32 v99, 0xffff0000, v141
	v_pk_fma_f32 v[144:145], v[40:41], v[144:145], 1.0 op_sel_hi:[1,1,0]
	v_add_f32_dpp v87, v87, v87 quad_perm:[1,0,3,2] row_mask:0xf bank_mask:0xf bound_ctrl:1
	v_pk_mul_f32 v[96:97], v[96:97], v[144:145]
	s_nop 0
	v_lshlrev_b32_e32 v146, 16, v139
	v_pk_mul_f32 v[144:145], v[90:91], v[96:97]
	v_add_f32_dpp v87, v87, v87 quad_perm:[2,3,0,1] row_mask:0xf bank_mask:0xf bound_ctrl:1
	v_mul_f32_e32 v145, v43, v145
	v_fmac_f32_e32 v145, v42, v144
	v_add_f32_dpp v87, v87, v87 row_half_mirror row_mask:0xf bank_mask:0xf bound_ctrl:1
	v_and_b32_e32 v147, 0xffff0000, v139
	v_add_f32_dpp v144, v145, v145 quad_perm:[1,0,3,2] row_mask:0xf bank_mask:0xf bound_ctrl:1
	v_add_f32_dpp v87, v87, v87 row_mirror row_mask:0xf bank_mask:0xf bound_ctrl:1
	ds_bpermute_b32 v143, v102, v87
	v_add_f32_dpp v144, v144, v144 quad_perm:[2,3,0,1] row_mask:0xf bank_mask:0xf bound_ctrl:1
	v_pk_add_f32 v[146:147], v[146:147], v[98:99] neg_lo:[0,1] neg_hi:[0,1]
	s_nop 0
	v_add_f32_dpp v144, v144, v144 row_half_mirror row_mask:0xf bank_mask:0xf bound_ctrl:1
	v_pk_fma_f32 v[98:99], v[34:35], v[146:147], v[98:99]
	s_nop 0
	v_add_f32_dpp v144, v144, v144 row_mirror row_mask:0xf bank_mask:0xf bound_ctrl:1
	ds_bpermute_b32 v145, v102, v144
	s_and_saveexec_b64 s[4:5], s[0:1]
	s_cbranch_execz .LBB0_980
	s_waitcnt lgkmcnt(0)
	v_add_f32_e32 v144, v144, v145
	v_pk_mul_f32 v[144:145], v[98:99], v[144:145] op_sel_hi:[1,0]
	s_nop 0
	v_and_b32_sdwa v147, v144, v135 dst_sel:DWORD dst_unused:UNUSED_PAD src0_sel:WORD_1 src1_sel:DWORD
	v_and_b32_sdwa v146, v145, v135 dst_sel:DWORD dst_unused:UNUSED_PAD src0_sel:WORD_1 src1_sel:DWORD
	v_add3_u32 v144, v144, v147, s6
	v_add3_u32 v145, v145, v146, s6
	v_lshrrev_b32_e32 v144, 16, v144
	v_and_or_b32 v146, v145, s31, v144
	v_lshl_add_u64 v[144:145], v[80:81], 0, s[16:17]
	global_store_dword v[144:145], v146, off
.LBB0_980:
	s_or_b64 exec, exec, s[4:5]
	s_waitcnt lgkmcnt(1)
	v_add_f32_e32 v87, v87, v143
	v_mul_f32_e32 v143, 0x4f800000, v87
	v_cmp_gt_f32_e32 vcc, s28, v87
	v_add3_u32 v44, s22, v110, v44
	ds_write2_b64 v44, v[88:89], v[96:97] offset1:32
	v_cndmask_b32_e32 v87, v87, v143, vcc
	v_sqrt_f32_e32 v143, v87
	ds_write2_b64 v44, v[90:91], v[98:99] offset0:128 offset1:160
	v_add_u32_e32 v144, -1, v143
	v_fma_f32 v146, -v144, v143, v87
	s_waitcnt lgkmcnt(2)
	v_add_u32_e32 v145, 1, v143
	v_cmp_ge_f32_e64 s[4:5], 0, v146
	s_nop 1
	v_cndmask_b32_e64 v144, v143, v144, s[4:5]
	v_fma_f32 v143, -v145, v143, v87
	v_cmp_lt_f32_e64 s[4:5], 0, v143
	s_nop 1
	v_cndmask_b32_e64 v143, v144, v145, s[4:5]
	v_mul_f32_e32 v144, 0x37800000, v143
	v_cndmask_b32_e32 v143, v143, v144, vcc
	v_cmp_class_f32_e32 vcc, v87, v103
	s_nop 1
	v_cndmask_b32_e32 v87, v143, v87, vcc
	v_max_f32_e32 v87, 0x2b8cbccc, v87
	v_div_scale_f32 v143, s[4:5], v87, v87, 1.0
	v_rcp_f32_e32 v144, v143
	s_add_i32 s4, s29, -1
	s_cmpk_lt_u32 s4, 0x7e
	v_fma_f32 v145, -v143, v144, 1.0
	v_fmac_f32_e32 v144, v145, v144
	v_div_scale_f32 v145, vcc, 1.0, v87, 1.0
	v_mul_f32_e32 v146, v145, v144
	v_fma_f32 v147, -v143, v146, v145
	v_fmac_f32_e32 v146, v147, v144
	v_fma_f32 v143, -v143, v146, v145
	v_div_fmas_f32 v143, v143, v144, v146
	v_div_fixup_f32 v144, v143, v87, 1.0
	v_pk_mul_f32 v[94:95], v[94:95], v[144:145] op_sel_hi:[1,0] neg_lo:[0,1] neg_hi:[0,1]
	s_nop 0
	v_pk_mul_f32 v[92:93], v[94:95], v[92:93] neg_lo:[1,0] neg_hi:[1,0]
	ds_write2_b64 v44, v[94:95], v[92:93] offset0:64 offset1:96
	s_cbranch_scc0 .LBB0_951
	s_cmp_lt_i32 s41, 0
	s_cbranch_scc1 .Lprep_w4
	s_waitcnt vmcnt(12)
	s_branch .Lprep_cp
.Lprep_w4:
	s_waitcnt vmcnt(4)
.Lprep_cp:
	v_mov_b64_e32 v[112:113], v[170:171]
	v_mov_b64_e32 v[114:115], v[172:173]
	v_mov_b64_e32 v[120:121], v[178:179]
	v_mov_b64_e32 v[122:123], v[180:181]
	v_mov_b64_e32 v[124:125], v[182:183]
	v_mov_b64_e32 v[126:127], v[184:185]
	v_mov_b64_e32 v[128:129], v[186:187]
	v_mov_b64_e32 v[130:131], v[188:189]
	v_mov_b64_e32 v[132:133], v[190:191]
	v_mov_b64_e32 v[136:137], v[194:195]
	v_mov_b64_e32 v[138:139], v[196:197]
	v_mov_b64_e32 v[140:141], v[198:199]
	v_mov_b32_e32 v116, v174
	v_mov_b32_e32 v119, v177
	v_mov_b32_e32 v134, v192
	v_mov_b32_e32 v142, v200
	v_mov_b64_e32 v[48:49], v[202:203]
	v_mov_b64_e32 v[50:51], v[204:205]
	v_mov_b64_e32 v[74:75], v[206:207]
	v_mov_b64_e32 v[88:89], v[208:209]
	v_lshl_add_u64 v[210:211], s[94:95], 0, v[56:57]
	v_lshl_add_u64 v[218:219], s[94:95], 0, v[52:53]
	v_add_co_u32_e32 v212, vcc, s34, v210
	v_lshl_add_u64 v[220:221], s[94:95], 0, v[54:55]
	s_nop 0
	v_addc_co_u32_e32 v213, vcc, 0, v211, vcc
	v_add_co_u32_e32 v214, vcc, s35, v210
	s_nop 1
	v_addc_co_u32_e32 v215, vcc, 0, v211, vcc
	v_add_co_u32_e32 v216, vcc, s39, v210
	s_nop 1
	v_addc_co_u32_e32 v217, vcc, 0, v211, vcc
	global_load_dword v170, v[212:213], off
	global_load_dword v171, v[212:213], off offset:2048
	global_load_dword v172, v[214:215], off
	global_load_dword v173, v[216:217], off offset:-2624
	global_load_dword v174, v[216:217], off offset:-576
	global_load_dword v177, v[212:213], off offset:-2624
	global_load_dwordx2 v[202:203], v[218:219], off
	global_load_dword v178, v[220:221], off
	v_lshl_add_u64 v[210:211], s[94:95], 0, v[62:63]
	v_lshl_add_u64 v[218:219], s[94:95], 0, v[58:59]
	v_add_co_u32_e32 v212, vcc, s34, v210
	v_lshl_add_u64 v[220:221], s[94:95], 0, v[60:61]
	s_nop 0
	v_addc_co_u32_e32 v213, vcc, 0, v211, vcc
	v_add_co_u32_e32 v214, vcc, s35, v210
	s_nop 1
	v_addc_co_u32_e32 v215, vcc, 0, v211, vcc
	v_add_co_u32_e32 v216, vcc, s39, v210
	s_nop 1
	v_addc_co_u32_e32 v217, vcc, 0, v211, vcc
	global_load_dword v186, v[212:213], off
	global_load_dword v179, v[212:213], off offset:2048
	global_load_dword v187, v[214:215], off
	global_load_dword v180, v[216:217], off offset:-2624
	global_load_dword v181, v[216:217], off offset:-576
	global_load_dword v182, v[212:213], off offset:-2624
	global_load_dwordx2 v[204:205], v[218:219], off
	global_load_dword v183, v[220:221], off
	v_lshl_add_u64 v[210:211], s[94:95], 0, v[68:69]
	v_lshl_add_u64 v[218:219], s[94:95], 0, v[64:65]
	v_add_co_u32_e32 v212, vcc, s34, v210
	v_lshl_add_u64 v[220:221], s[94:95], 0, v[66:67]
	s_nop 0
	v_addc_co_u32_e32 v213, vcc, 0, v211, vcc
	v_add_co_u32_e32 v214, vcc, s35, v210
	s_nop 1
	v_addc_co_u32_e32 v215, vcc, 0, v211, vcc
	v_add_co_u32_e32 v216, vcc, s39, v210
	s_nop 1
	v_addc_co_u32_e32 v217, vcc, 0, v211, vcc
	global_load_dword v191, v[212:213], off
	global_load_dword v184, v[212:213], off offset:2048
	global_load_dword v192, v[214:215], off
	global_load_dword v185, v[216:217], off offset:-2624
	global_load_dword v188, v[216:217], off offset:-576
	global_load_dword v189, v[212:213], off offset:-2624
	global_load_dwordx2 v[206:207], v[218:219], off
	global_load_dword v190, v[220:221], off
	v_lshl_add_u64 v[210:211], s[94:95], 0, v[76:77]
	v_lshl_add_u64 v[218:219], s[94:95], 0, v[70:71]
	v_add_co_u32_e32 v212, vcc, s34, v210
	v_lshl_add_u64 v[220:221], s[94:95], 0, v[72:73]
	s_nop 0
	v_addc_co_u32_e32 v213, vcc, 0, v211, vcc
	v_add_co_u32_e32 v214, vcc, s35, v210
	s_nop 1
	v_addc_co_u32_e32 v215, vcc, 0, v211, vcc
	v_add_co_u32_e32 v216, vcc, s39, v210
	s_nop 1
	v_addc_co_u32_e32 v217, vcc, 0, v211, vcc
	global_load_dword v198, v[212:213], off
	global_load_dword v194, v[212:213], off offset:2048
	global_load_dword v199, v[214:215], off
	global_load_dword v195, v[216:217], off offset:-2624
	global_load_dword v196, v[216:217], off offset:-576
	global_load_dword v197, v[212:213], off offset:-2624
	global_load_dwordx2 v[208:209], v[218:219], off
	global_load_dword v200, v[220:221], off
	s_branch .LBB0_951
